# DFTS-Q epilogue: P loads prefetched a whole group ahead into dead accumulator regs, counted vmcnt, flat->global; nothing else changed
# baseline (speedup 1.0000x reference)
.LBB0_126:
	s_add_u32 s0, s8, 0xfff80080
	s_addc_u32 s1, s9, -1
	s_add_i32 s2, 0, 0x10000
	v_add_u32_e32 v138, s2, v238
	ds_read_b128 v[154:157], v138
	ds_read_b128 v[158:161], v138 offset:1024
	ds_read_b128 v[162:165], v138 offset:2048
	ds_read_b128 v[166:169], v138 offset:3072
	s_cmp_eq_u32 s20, 28
	s_cselect_b32 s11, s45, s1
	s_cselect_b32 s10, s44, s0
	s_cselect_b32 s1, s67, s15
	s_cselect_b32 s0, s66, s13
	v_lshl_add_u64 v[138:139], s[8:9], 0, v[136:137]
	s_add_i32 m0, s17, 0xc000
	ds_read_b128 v[170:173], v239
	ds_read_b128 v[174:177], v239 offset:1024
	ds_read_b128 v[178:181], v239 offset:2048
	ds_read_b128 v[182:185], v239 offset:3072
	ds_read_b128 v[186:189], v239 offset:4096
	ds_read_b128 v[190:193], v239 offset:5120
	ds_read_b128 v[194:197], v239 offset:6144
	ds_read_b128 v[198:201], v239 offset:7168
	global_load_lds_dwordx4 v[138:139], off
	v_lshl_add_u64 v[138:139], s[8:9], 0, v[134:135]
	s_add_i32 m0, s17, 0xe000
	s_nop 0
	global_load_lds_dwordx4 v[138:139], off
	s_waitcnt lgkmcnt(8)
	s_barrier
	s_waitcnt lgkmcnt(0)
	s_setprio 1
	s_waitcnt lgkmcnt(0)
	v_mfma_f32_16x16x32_bf16 v[124:127], v[154:157], v[170:173], v[124:127]
	v_mfma_f32_16x16x32_bf16 v[120:123], v[162:165], v[170:173], v[120:123]
	v_mfma_f32_16x16x32_bf16 v[116:119], v[154:157], v[178:181], v[116:119]
	v_mfma_f32_16x16x32_bf16 v[112:115], v[162:165], v[178:181], v[112:115]
	v_mfma_f32_16x16x32_bf16 v[104:107], v[154:157], v[186:189], v[104:107]
	v_mfma_f32_16x16x32_bf16 v[96:99], v[162:165], v[186:189], v[96:99]
	v_mfma_f32_16x16x32_bf16 v[88:91], v[154:157], v[194:197], v[88:91]
	v_mfma_f32_16x16x32_bf16 v[80:83], v[162:165], v[194:197], v[80:83]
	v_mfma_f32_16x16x32_bf16 v[124:127], v[158:161], v[174:177], v[124:127]
	v_mfma_f32_16x16x32_bf16 v[120:123], v[166:169], v[174:177], v[120:123]
	v_mfma_f32_16x16x32_bf16 v[116:119], v[158:161], v[182:185], v[116:119]
	v_mfma_f32_16x16x32_bf16 v[112:115], v[166:169], v[182:185], v[112:115]
	v_mfma_f32_16x16x32_bf16 v[104:107], v[158:161], v[190:193], v[104:107]
	v_mfma_f32_16x16x32_bf16 v[96:99], v[166:169], v[190:193], v[96:99]
	v_mfma_f32_16x16x32_bf16 v[88:91], v[158:161], v[198:201], v[88:91]
	v_mfma_f32_16x16x32_bf16 v[80:83], v[166:169], v[198:201], v[80:83]
	s_setprio 0
	s_barrier
	s_add_i32 s21, 0, 0x14000
	v_add_u32_e32 v138, s21, v238
	s_add_i32 s2, s2, s58
	ds_read_b128 v[202:205], v138
	ds_read_b128 v[206:209], v138 offset:1024
	ds_read_b128 v[240:243], v138 offset:2048
	ds_read_b128 v[244:247], v138 offset:3072
	v_lshl_add_u64 v[138:139], s[0:1], 0, v[140:141]
	s_mov_b32 m0, s2
	v_lshl_add_u64 v[210:211], s[0:1], 0, v[132:133]
	global_load_lds_dwordx4 v[138:139], off
	s_add_i32 m0, s2, 0x2000
	s_nop 0
	global_load_lds_dwordx4 v[210:211], off
	s_barrier
	s_waitcnt lgkmcnt(0)
	s_setprio 1
	s_waitcnt lgkmcnt(0)
	v_mfma_f32_16x16x32_bf16 v[108:111], v[202:205], v[170:173], v[108:111]
	v_mfma_f32_16x16x32_bf16 v[100:103], v[240:243], v[170:173], v[100:103]
	v_mfma_f32_16x16x32_bf16 v[92:95], v[202:205], v[178:181], v[92:95]
	v_mfma_f32_16x16x32_bf16 v[84:87], v[240:243], v[178:181], v[84:87]
	v_mfma_f32_16x16x32_bf16 v[76:79], v[202:205], v[186:189], v[76:79]
	v_mfma_f32_16x16x32_bf16 v[72:75], v[240:243], v[186:189], v[72:75]
	v_mfma_f32_16x16x32_bf16 v[68:71], v[202:205], v[194:197], v[68:71]
	v_mfma_f32_16x16x32_bf16 v[64:67], v[240:243], v[194:197], v[64:67]
	v_mfma_f32_16x16x32_bf16 v[108:111], v[206:209], v[174:177], v[108:111]
	v_mfma_f32_16x16x32_bf16 v[100:103], v[244:247], v[174:177], v[100:103]
	v_mfma_f32_16x16x32_bf16 v[92:95], v[206:209], v[182:185], v[92:95]
	v_mfma_f32_16x16x32_bf16 v[84:87], v[244:247], v[182:185], v[84:87]
	v_mfma_f32_16x16x32_bf16 v[76:79], v[206:209], v[190:193], v[76:79]
	v_mfma_f32_16x16x32_bf16 v[72:75], v[244:247], v[190:193], v[72:75]
	v_mfma_f32_16x16x32_bf16 v[68:71], v[206:209], v[198:201], v[68:71]
	v_mfma_f32_16x16x32_bf16 v[64:67], v[244:247], v[198:201], v[64:67]
	s_setprio 0
	s_mov_b32 m0, s17
	v_lshl_add_u64 v[248:249], s[10:11], 0, v[128:129]
	s_barrier
	ds_read_b128 v[170:173], v239 offset:16384
	ds_read_b128 v[174:177], v239 offset:17408
	ds_read_b128 v[178:181], v239 offset:18432
	ds_read_b128 v[182:185], v239 offset:19456
	ds_read_b128 v[186:189], v239 offset:20480
	ds_read_b128 v[190:193], v239 offset:21504
	ds_read_b128 v[194:197], v239 offset:22528
	ds_read_b128 v[198:201], v239 offset:23552
	global_load_lds_dwordx4 v[248:249], off
	v_lshl_add_u64 v[250:251], s[10:11], 0, v[130:131]
	s_mov_b32 m0, s59
	s_nop 0
	global_load_lds_dwordx4 v[250:251], off
	s_barrier
	s_waitcnt lgkmcnt(0)
	s_setprio 1
	s_waitcnt lgkmcnt(0)
	v_mfma_f32_16x16x32_bf16 v[60:63], v[154:157], v[170:173], v[60:63]
	v_mfma_f32_16x16x32_bf16 v[56:59], v[162:165], v[170:173], v[56:59]
	v_mfma_f32_16x16x32_bf16 v[52:55], v[154:157], v[178:181], v[52:55]
	v_mfma_f32_16x16x32_bf16 v[48:51], v[162:165], v[178:181], v[48:51]
	v_mfma_f32_16x16x32_bf16 v[36:39], v[154:157], v[186:189], v[36:39]
	v_mfma_f32_16x16x32_bf16 v[32:35], v[162:165], v[186:189], v[32:35]
	v_mfma_f32_16x16x32_bf16 v[20:23], v[154:157], v[194:197], v[20:23]
	v_mfma_f32_16x16x32_bf16 v[16:19], v[162:165], v[194:197], v[16:19]
	v_mfma_f32_16x16x32_bf16 v[60:63], v[158:161], v[174:177], v[60:63]
	v_mfma_f32_16x16x32_bf16 v[56:59], v[166:169], v[174:177], v[56:59]
	v_mfma_f32_16x16x32_bf16 v[52:55], v[158:161], v[182:185], v[52:55]
	v_mfma_f32_16x16x32_bf16 v[48:51], v[166:169], v[182:185], v[48:51]
	v_mfma_f32_16x16x32_bf16 v[36:39], v[158:161], v[190:193], v[36:39]
	v_mfma_f32_16x16x32_bf16 v[32:35], v[166:169], v[190:193], v[32:35]
	v_mfma_f32_16x16x32_bf16 v[20:23], v[158:161], v[198:201], v[20:23]
	v_mfma_f32_16x16x32_bf16 v[16:19], v[166:169], v[198:201], v[16:19]
	s_setprio 0
	s_barrier
	s_add_u32 s18, s0, 0x100000
	s_addc_u32 s19, s1, 0
	s_add_i32 s2, s21, s58
	v_lshl_add_u64 v[154:155], s[18:19], 0, v[140:141]
	s_mov_b32 m0, s2
	s_nop 0
	global_load_lds_dwordx4 v[154:155], off
	v_lshl_add_u64 v[154:155], s[18:19], 0, v[132:133]
	s_add_i32 m0, s2, 0x2000
	s_nop 0
	global_load_lds_dwordx4 v[154:155], off
	s_waitcnt vmcnt(6)
	s_barrier
	s_setprio 1
	v_mfma_f32_16x16x32_bf16 v[44:47], v[202:205], v[170:173], v[44:47]
	v_mfma_f32_16x16x32_bf16 v[40:43], v[240:243], v[170:173], v[40:43]
	v_mfma_f32_16x16x32_bf16 v[28:31], v[202:205], v[178:181], v[28:31]
	v_mfma_f32_16x16x32_bf16 v[24:27], v[240:243], v[178:181], v[24:27]
	v_mfma_f32_16x16x32_bf16 v[12:15], v[202:205], v[186:189], v[12:15]
	v_mfma_f32_16x16x32_bf16 v[8:11], v[240:243], v[186:189], v[8:11]
	v_mfma_f32_16x16x32_bf16 v[4:7], v[202:205], v[194:197], v[4:7]
	v_mfma_f32_16x16x32_bf16 v[0:3], v[240:243], v[194:197], v[0:3]
	v_mfma_f32_16x16x32_bf16 v[44:47], v[206:209], v[174:177], v[44:47]
	v_mfma_f32_16x16x32_bf16 v[40:43], v[244:247], v[174:177], v[40:43]
	v_mfma_f32_16x16x32_bf16 v[28:31], v[206:209], v[182:185], v[28:31]
	v_mfma_f32_16x16x32_bf16 v[24:27], v[244:247], v[182:185], v[24:27]
	v_mfma_f32_16x16x32_bf16 v[12:15], v[206:209], v[190:193], v[12:15]
	v_mfma_f32_16x16x32_bf16 v[8:11], v[244:247], v[190:193], v[8:11]
	v_mfma_f32_16x16x32_bf16 v[4:7], v[206:209], v[198:201], v[4:7]
	v_mfma_f32_16x16x32_bf16 v[0:3], v[244:247], v[198:201], v[0:3]
	s_setprio 0
	s_add_i32 s2, 0, 0x18000
	v_add_u32_e32 v166, s2, v238
	s_barrier
	ds_read_b128 v[154:157], v166
	ds_read_b128 v[158:161], v166 offset:1024
	ds_read_b128 v[162:165], v166 offset:2048
	ds_read_b128 v[166:169], v166 offset:3072
	s_add_u32 s10, s10, 0x80000
	s_addc_u32 s11, s11, 0
	s_mov_b32 m0, s65
	v_lshl_add_u64 v[202:203], s[10:11], 0, v[128:129]
	ds_read_b128 v[170:173], v239 offset:32768
	ds_read_b128 v[174:177], v239 offset:33792
	ds_read_b128 v[178:181], v239 offset:34816
	ds_read_b128 v[182:185], v239 offset:35840
	ds_read_b128 v[186:189], v239 offset:36864
	ds_read_b128 v[190:193], v239 offset:37888
	ds_read_b128 v[194:197], v239 offset:38912
	ds_read_b128 v[198:201], v239 offset:39936
	global_load_lds_dwordx4 v[202:203], off
	v_lshl_add_u64 v[202:203], s[10:11], 0, v[130:131]
	s_mov_b32 m0, s72
	s_nop 0
	global_load_lds_dwordx4 v[202:203], off
	s_waitcnt lgkmcnt(8)
	s_barrier
	s_waitcnt lgkmcnt(0)
	s_setprio 1
	s_waitcnt lgkmcnt(0)
	v_mfma_f32_16x16x32_bf16 v[124:127], v[154:157], v[170:173], v[124:127]
	v_mfma_f32_16x16x32_bf16 v[120:123], v[162:165], v[170:173], v[120:123]
	v_mfma_f32_16x16x32_bf16 v[116:119], v[154:157], v[178:181], v[116:119]
	v_mfma_f32_16x16x32_bf16 v[112:115], v[162:165], v[178:181], v[112:115]
	v_mfma_f32_16x16x32_bf16 v[104:107], v[154:157], v[186:189], v[104:107]
	v_mfma_f32_16x16x32_bf16 v[96:99], v[162:165], v[186:189], v[96:99]
	v_mfma_f32_16x16x32_bf16 v[88:91], v[154:157], v[194:197], v[88:91]
	v_mfma_f32_16x16x32_bf16 v[80:83], v[162:165], v[194:197], v[80:83]
	v_mfma_f32_16x16x32_bf16 v[124:127], v[158:161], v[174:177], v[124:127]
	v_mfma_f32_16x16x32_bf16 v[120:123], v[166:169], v[174:177], v[120:123]
	v_mfma_f32_16x16x32_bf16 v[116:119], v[158:161], v[182:185], v[116:119]
	v_mfma_f32_16x16x32_bf16 v[112:115], v[166:169], v[182:185], v[112:115]
	v_mfma_f32_16x16x32_bf16 v[104:107], v[158:161], v[190:193], v[104:107]
	v_mfma_f32_16x16x32_bf16 v[96:99], v[166:169], v[190:193], v[96:99]
	v_mfma_f32_16x16x32_bf16 v[88:91], v[158:161], v[198:201], v[88:91]
	v_mfma_f32_16x16x32_bf16 v[80:83], v[166:169], v[198:201], v[80:83]
	s_setprio 0
	s_barrier
	s_add_i32 s10, 0, 0x1c000
	s_add_i32 s2, s2, s58
	v_add_u32_e32 v244, s10, v238
	v_lshl_add_u64 v[138:139], v[138:139], 0, s[82:83]
	s_mov_b32 m0, s2
	ds_read_b128 v[202:205], v244
	ds_read_b128 v[206:209], v244 offset:1024
	ds_read_b128 v[240:243], v244 offset:2048
	ds_read_b128 v[244:247], v244 offset:3072
	global_load_lds_dwordx4 v[138:139], off
	v_lshl_add_u64 v[138:139], v[210:211], 0, s[82:83]
	s_add_i32 m0, s2, 0x2000
	s_nop 0
	global_load_lds_dwordx4 v[138:139], off
	s_barrier
	s_waitcnt lgkmcnt(0)
	s_setprio 1
	s_waitcnt lgkmcnt(0)
	v_mfma_f32_16x16x32_bf16 v[108:111], v[202:205], v[170:173], v[108:111]
	v_mfma_f32_16x16x32_bf16 v[100:103], v[240:243], v[170:173], v[100:103]
	v_mfma_f32_16x16x32_bf16 v[92:95], v[202:205], v[178:181], v[92:95]
	v_mfma_f32_16x16x32_bf16 v[84:87], v[240:243], v[178:181], v[84:87]
	v_mfma_f32_16x16x32_bf16 v[76:79], v[202:205], v[186:189], v[76:79]
	v_mfma_f32_16x16x32_bf16 v[72:75], v[240:243], v[186:189], v[72:75]
	v_mfma_f32_16x16x32_bf16 v[68:71], v[202:205], v[194:197], v[68:71]
	v_mfma_f32_16x16x32_bf16 v[64:67], v[240:243], v[194:197], v[64:67]
	v_mfma_f32_16x16x32_bf16 v[108:111], v[206:209], v[174:177], v[108:111]
	v_mfma_f32_16x16x32_bf16 v[100:103], v[244:247], v[174:177], v[100:103]
	v_mfma_f32_16x16x32_bf16 v[92:95], v[206:209], v[182:185], v[92:95]
	v_mfma_f32_16x16x32_bf16 v[84:87], v[244:247], v[182:185], v[84:87]
	v_mfma_f32_16x16x32_bf16 v[76:79], v[206:209], v[190:193], v[76:79]
	v_mfma_f32_16x16x32_bf16 v[72:75], v[244:247], v[190:193], v[72:75]
	v_mfma_f32_16x16x32_bf16 v[68:71], v[206:209], v[198:201], v[68:71]
	v_mfma_f32_16x16x32_bf16 v[64:67], v[244:247], v[198:201], v[64:67]
	s_setprio 0
	s_mov_b32 m0, s75
	v_lshl_add_u64 v[138:139], v[248:249], 0, s[82:83]
	s_barrier
	ds_read_b128 v[170:173], v239 offset:49152
	ds_read_b128 v[174:177], v239 offset:50176
	ds_read_b128 v[178:181], v239 offset:51200
	ds_read_b128 v[182:185], v239 offset:52224
	ds_read_b128 v[186:189], v239 offset:53248
	ds_read_b128 v[190:193], v239 offset:54272
	ds_read_b128 v[194:197], v239 offset:55296
	ds_read_b128 v[198:201], v239 offset:56320
	global_load_lds_dwordx4 v[138:139], off
	v_lshl_add_u64 v[138:139], v[250:251], 0, s[82:83]
	s_mov_b32 m0, s77
	s_nop 0
	global_load_lds_dwordx4 v[138:139], off
	s_barrier
	s_waitcnt lgkmcnt(0)
	s_setprio 1
	s_waitcnt lgkmcnt(0)
	v_mfma_f32_16x16x32_bf16 v[60:63], v[154:157], v[170:173], v[60:63]
	v_mfma_f32_16x16x32_bf16 v[56:59], v[162:165], v[170:173], v[56:59]
	v_mfma_f32_16x16x32_bf16 v[52:55], v[154:157], v[178:181], v[52:55]
	v_mfma_f32_16x16x32_bf16 v[48:51], v[162:165], v[178:181], v[48:51]
	v_mfma_f32_16x16x32_bf16 v[36:39], v[154:157], v[186:189], v[36:39]
	v_mfma_f32_16x16x32_bf16 v[32:35], v[162:165], v[186:189], v[32:35]
	v_mfma_f32_16x16x32_bf16 v[20:23], v[154:157], v[194:197], v[20:23]
	v_mfma_f32_16x16x32_bf16 v[16:19], v[162:165], v[194:197], v[16:19]
	v_mfma_f32_16x16x32_bf16 v[60:63], v[158:161], v[174:177], v[60:63]
	v_mfma_f32_16x16x32_bf16 v[56:59], v[166:169], v[174:177], v[56:59]
	v_mfma_f32_16x16x32_bf16 v[52:55], v[158:161], v[182:185], v[52:55]
	v_mfma_f32_16x16x32_bf16 v[48:51], v[166:169], v[182:185], v[48:51]
	v_mfma_f32_16x16x32_bf16 v[36:39], v[158:161], v[190:193], v[36:39]
	v_mfma_f32_16x16x32_bf16 v[32:35], v[166:169], v[190:193], v[32:35]
	v_mfma_f32_16x16x32_bf16 v[20:23], v[158:161], v[198:201], v[20:23]
	v_mfma_f32_16x16x32_bf16 v[16:19], v[166:169], v[198:201], v[16:19]
	s_setprio 0
	s_barrier
	s_add_u32 s0, s0, 0x100080
	s_addc_u32 s1, s1, 0
	s_add_i32 s2, s10, s58
	v_lshl_add_u64 v[138:139], s[0:1], 0, v[140:141]
	s_mov_b32 m0, s2
	s_nop 0
	global_load_lds_dwordx4 v[138:139], off
	v_lshl_add_u64 v[138:139], s[0:1], 0, v[132:133]
	s_add_i32 m0, s2, 0x2000
	s_nop 0
	global_load_lds_dwordx4 v[138:139], off
	s_waitcnt vmcnt(6)
	s_barrier
	s_setprio 1
	v_mfma_f32_16x16x32_bf16 v[44:47], v[202:205], v[170:173], v[44:47]
	v_mfma_f32_16x16x32_bf16 v[40:43], v[240:243], v[170:173], v[40:43]
	v_mfma_f32_16x16x32_bf16 v[28:31], v[202:205], v[178:181], v[28:31]
	v_mfma_f32_16x16x32_bf16 v[24:27], v[240:243], v[178:181], v[24:27]
	v_mfma_f32_16x16x32_bf16 v[12:15], v[202:205], v[186:189], v[12:15]
	v_mfma_f32_16x16x32_bf16 v[8:11], v[240:243], v[186:189], v[8:11]
	v_mfma_f32_16x16x32_bf16 v[4:7], v[202:205], v[194:197], v[4:7]
	v_mfma_f32_16x16x32_bf16 v[0:3], v[240:243], v[194:197], v[0:3]
	v_mfma_f32_16x16x32_bf16 v[44:47], v[206:209], v[174:177], v[44:47]
	v_mfma_f32_16x16x32_bf16 v[40:43], v[244:247], v[174:177], v[40:43]
	v_mfma_f32_16x16x32_bf16 v[28:31], v[206:209], v[182:185], v[28:31]
	v_mfma_f32_16x16x32_bf16 v[24:27], v[244:247], v[182:185], v[24:27]
	v_mfma_f32_16x16x32_bf16 v[12:15], v[206:209], v[190:193], v[12:15]
	v_mfma_f32_16x16x32_bf16 v[8:11], v[244:247], v[190:193], v[8:11]
	v_mfma_f32_16x16x32_bf16 v[4:7], v[206:209], v[198:201], v[4:7]
	v_mfma_f32_16x16x32_bf16 v[0:3], v[244:247], v[198:201], v[0:3]
	s_setprio 0
	s_add_i32 s20, s20, 2
	s_add_u32 s13, s13, 0x100
	s_addc_u32 s15, s15, 0
	s_add_u32 s8, s8, 0x100
	s_addc_u32 s9, s9, 0
	s_cmp_gt_u32 s20, 29
	s_barrier
	s_cbranch_scc0 .LBB0_126
	v_mbcnt_lo_u32_b32 v154, -1, 0
	v_mbcnt_hi_u32_b32 v154, -1, v154
	s_lshl_b32 s0, s16, 8
	v_ashrrev_i32_e32 v138, 2, v154
	s_or_b32 s0, s0, s74
	v_and_b32_e32 v138, -4, v138
	s_lshl_b32 s13, s64, 8
	v_add_u32_e32 v138, s0, v138
	v_and_b32_e32 v240, 15, v154
	s_cmp_gt_i32 s71, 7
	s_mov_b64 s[0:1], -1
	v_ashrrev_i32_e32 v139, 31, v138
	s_cbranch_scc0 .LBB0_145
	s_add_i32 s0, s71, -8
	s_lshl_b32 s52, s0, 10
	s_lshl_b32 s15, s0, 12
	s_lshl_b32 s16, s0, 11
	s_addk_i32 s15, 0x1000
	s_lshl_b64 s[0:1], s[52:53], 2
	v_or_b32_e32 v155, s73, v240
	s_add_u32 s0, s49, s0
	v_add_u32_e32 v206, s13, v155
	s_addc_u32 s1, s76, s1
	v_lshlrev_b64 v[198:199], 2, v[138:139]
	v_add_u32_e32 v156, s16, v206
	v_lshl_add_u64 v[160:161], s[0:1], 0, v[198:199]
	v_ashrrev_i32_e32 v157, 31, v156
	flat_load_dwordx4 v[162:165], v[160:161]
	v_lshlrev_b64 v[158:159], 12, v[156:157]
	v_lshl_add_u64 v[158:159], s[26:27], 0, v[158:159]
	v_lshl_add_u64 v[158:159], v[158:159], 0, v[198:199]
	flat_load_dwordx4 v[166:169], v[158:159] nt
	s_mov_b32 s0, 0x3c800000
	v_and_b32_e32 v155, 1, v154
	v_add_u32_e32 v156, s16, v156
	v_cmp_eq_u32_e64 s[8:9], 0, v155
	v_ashrrev_i32_e32 v157, 31, v156
	v_lshlrev_b64 v[156:157], 11, v[156:157]
	v_sub_u32_e32 v154, s15, v206
	v_lshl_add_u64 v[156:157], s[24:25], 0, v[156:157]
	v_cmp_ne_u32_e32 vcc, 0, v206
	v_lshl_add_u64 v[156:157], v[138:139], 1, v[156:157]
	s_waitcnt vmcnt(0) lgkmcnt(0)
	v_or_b32_e32 v236, 16, v206
	v_add_u32_e32 v236, s16, v236
	v_ashrrev_i32_e32 v237, 31, v236
	v_lshlrev_b64 v[236:237], 12, v[236:237]
	v_lshl_add_u64 v[236:237], s[26:27], 0, v[236:237]
	v_lshl_add_u64 v[236:237], v[236:237], 0, v[198:199]
	global_load_dwordx4 v[232:235], v[236:237], off nt
	v_or_b32_e32 v236, 32, v206
	v_add_u32_e32 v236, s16, v236
	v_ashrrev_i32_e32 v237, 31, v236
	v_lshlrev_b64 v[236:237], 12, v[236:237]
	v_lshl_add_u64 v[236:237], s[26:27], 0, v[236:237]
	v_lshl_add_u64 v[236:237], v[236:237], 0, v[198:199]
	global_load_dwordx4 v[246:249], v[236:237], off nt
	v_pk_mul_f32 v[164:165], v[164:165], s[0:1] op_sel_hi:[1,0]
	v_pk_mul_f32 v[162:163], v[162:163], s[0:1] op_sel_hi:[1,0]
	v_xor_b32_e32 v170, 0x80000000, v164
	v_xor_b32_e32 v171, 0x80000000, v165
	v_xor_b32_e32 v172, 0x80000000, v162
	v_xor_b32_e32 v173, 0x80000000, v163
	v_cndmask_b32_e64 v201, v171, v165, s[8:9]
	v_cndmask_b32_e64 v200, v170, v164, s[8:9]
	v_cndmask_b32_e64 v205, v173, v163, s[8:9]
	v_cndmask_b32_e64 v204, v172, v162, s[8:9]
	v_pk_add_f32 v[162:163], v[168:169], v[200:201]
	v_pk_add_f32 v[164:165], v[166:167], v[204:205]
	v_sub_f32_e32 v155, v162, v126
	v_sub_f32_e32 v167, v163, v127
	v_sub_f32_e32 v166, v164, v124
	v_cvt_pk_bf16_f32 v167, v155, v167
	v_ashrrev_i32_e32 v155, 31, v154
	v_sub_f32_e32 v168, v165, v125
	v_cvt_pk_bf16_f32 v166, v166, v168
	global_store_dwordx2 v[156:157], v[166:167], off
	s_and_saveexec_b64 s[0:1], vcc
	s_cbranch_execz .LBB0_130
	v_pk_add_f32 v[162:163], v[126:127], v[162:163]
	v_pk_add_f32 v[164:165], v[124:125], v[164:165]
	s_nop 0
	v_cvt_pk_bf16_f32 v164, v164, v165
	v_cvt_pk_bf16_f32 v165, v162, v163
	v_lshlrev_b64 v[162:163], 11, v[154:155]
	v_lshl_add_u64 v[162:163], s[24:25], 0, v[162:163]
	v_lshl_add_u64 v[162:163], v[138:139], 1, v[162:163]
	global_store_dwordx2 v[162:163], v[164:165], off
.LBB0_130:
	s_or_b64 exec, exec, s[0:1]
	v_or_b32_e32 v174, 16, v206
	v_add_u32_e32 v168, s16, v174
	v_ashrrev_i32_e32 v169, 31, v168
	v_lshlrev_b64 v[162:163], 12, v[168:169]
	v_lshl_add_u64 v[162:163], s[26:27], 0, v[162:163]
	v_lshl_add_u64 v[162:163], v[162:163], 0, v[198:199]
	s_waitcnt vmcnt(3)
	v_mov_b64_e32 v[164:165], v[232:233]
	v_mov_b64_e32 v[166:167], v[234:235]
	v_or_b32_e32 v236, 48, v206
	v_add_u32_e32 v236, s16, v236
	v_ashrrev_i32_e32 v237, 31, v236
	v_lshlrev_b64 v[236:237], 12, v[236:237]
	v_lshl_add_u64 v[236:237], s[26:27], 0, v[236:237]
	v_lshl_add_u64 v[236:237], v[236:237], 0, v[198:199]
	global_load_dwordx4 v[228:231], v[236:237], off nt
	v_or_b32_e32 v180, 32, v206
	v_lshlrev_b64 v[202:203], 1, v[138:139]
	v_or_b32_e32 v186, 48, v206
	v_add_u32_e32 v192, 0x80, v206
	v_add_u32_e32 v190, s16, v192
	v_ashrrev_i32_e32 v191, 31, v190
	v_cmp_ne_u32_e64 s[10:11], 0, v192
	v_pk_add_f32 v[170:171], v[200:201], v[166:167]
	v_pk_add_f32 v[164:165], v[204:205], v[164:165]
	v_sub_f32_e32 v166, v170, v118
	v_sub_f32_e32 v169, v164, v116
	v_sub_f32_e32 v172, v165, v117
	v_pk_add_f32 v[164:165], v[116:117], v[164:165]
	v_sub_f32_e32 v167, v171, v119
	v_cvt_pk_bf16_f32 v172, v169, v172
	v_cvt_pk_bf16_f32 v173, v166, v167
	v_add_u32_e32 v166, s16, v168
	v_pk_add_f32 v[168:169], v[118:119], v[170:171]
	v_cvt_pk_bf16_f32 v170, v164, v165
	v_sub_u32_e32 v164, s15, v174
	v_ashrrev_i32_e32 v167, 31, v166
	v_ashrrev_i32_e32 v165, 31, v164
	v_lshlrev_b64 v[166:167], 11, v[166:167]
	v_lshlrev_b64 v[164:165], 11, v[164:165]
	v_add_u32_e32 v174, s16, v180
	v_lshl_add_u64 v[166:167], s[24:25], 0, v[166:167]
	v_lshl_add_u64 v[164:165], s[24:25], 0, v[164:165]
	v_ashrrev_i32_e32 v175, 31, v174
	v_lshl_add_u64 v[166:167], v[166:167], 0, v[202:203]
	v_cvt_pk_bf16_f32 v171, v168, v169
	v_lshl_add_u64 v[164:165], v[164:165], 0, v[202:203]
	v_lshlrev_b64 v[168:169], 12, v[174:175]
	global_store_dwordx2 v[166:167], v[172:173], off
	global_store_dwordx2 v[164:165], v[170:171], off
	v_lshl_add_u64 v[168:169], s[26:27], 0, v[168:169]
	v_lshl_add_u64 v[168:169], v[168:169], 0, v[198:199]
	s_waitcnt vmcnt(5)
	v_mov_b64_e32 v[170:171], v[246:247]
	v_mov_b64_e32 v[172:173], v[248:249]
	v_add_u32_e32 v236, 0x80, v206
	v_add_u32_e32 v236, s16, v236
	v_ashrrev_i32_e32 v237, 31, v236
	v_lshlrev_b64 v[236:237], 12, v[236:237]
	v_lshl_add_u64 v[236:237], s[26:27], 0, v[236:237]
	v_lshl_add_u64 v[236:237], v[236:237], 0, v[198:199]
	global_load_dwordx4 v[232:235], v[236:237], off nt
	v_pk_add_f32 v[176:177], v[200:201], v[172:173]
	v_pk_add_f32 v[170:171], v[204:205], v[170:171]
	v_sub_f32_e32 v172, v176, v106
	v_sub_f32_e32 v175, v170, v104
	v_sub_f32_e32 v178, v171, v105
	v_pk_add_f32 v[170:171], v[104:105], v[170:171]
	v_sub_f32_e32 v173, v177, v107
	v_cvt_pk_bf16_f32 v178, v175, v178
	v_cvt_pk_bf16_f32 v179, v172, v173
	v_add_u32_e32 v172, s16, v174
	v_pk_add_f32 v[174:175], v[106:107], v[176:177]
	v_cvt_pk_bf16_f32 v176, v170, v171
	v_sub_u32_e32 v170, s15, v180
	v_ashrrev_i32_e32 v173, 31, v172
	v_ashrrev_i32_e32 v171, 31, v170
	v_lshlrev_b64 v[172:173], 11, v[172:173]
	v_lshlrev_b64 v[170:171], 11, v[170:171]
	v_add_u32_e32 v180, s16, v186
	v_lshl_add_u64 v[172:173], s[24:25], 0, v[172:173]
	v_lshl_add_u64 v[170:171], s[24:25], 0, v[170:171]
	v_ashrrev_i32_e32 v181, 31, v180
	v_lshl_add_u64 v[172:173], v[172:173], 0, v[202:203]
	v_cvt_pk_bf16_f32 v177, v174, v175
	v_lshl_add_u64 v[170:171], v[170:171], 0, v[202:203]
	v_lshlrev_b64 v[174:175], 12, v[180:181]
	global_store_dwordx2 v[172:173], v[178:179], off
	global_store_dwordx2 v[170:171], v[176:177], off
	v_lshl_add_u64 v[174:175], s[26:27], 0, v[174:175]
	v_lshl_add_u64 v[174:175], v[174:175], 0, v[198:199]
	s_waitcnt vmcnt(5)
	v_mov_b64_e32 v[176:177], v[228:229]
	v_mov_b64_e32 v[178:179], v[230:231]
	v_add_u32_e32 v236, 0x90, v206
	v_add_u32_e32 v236, s16, v236
	v_ashrrev_i32_e32 v237, 31, v236
	v_lshlrev_b64 v[236:237], 12, v[236:237]
	v_lshl_add_u64 v[236:237], s[26:27], 0, v[236:237]
	v_lshl_add_u64 v[236:237], v[236:237], 0, v[198:199]
	global_load_dwordx4 v[246:249], v[236:237], off nt
	v_pk_add_f32 v[182:183], v[200:201], v[178:179]
	v_pk_add_f32 v[176:177], v[204:205], v[176:177]
	v_sub_f32_e32 v178, v182, v90
	v_sub_f32_e32 v181, v176, v88
	v_sub_f32_e32 v184, v177, v89
	v_pk_add_f32 v[176:177], v[88:89], v[176:177]
	v_sub_f32_e32 v179, v183, v91
	v_cvt_pk_bf16_f32 v184, v181, v184
	v_cvt_pk_bf16_f32 v185, v178, v179
	v_add_u32_e32 v178, s16, v180
	v_pk_add_f32 v[180:181], v[90:91], v[182:183]
	v_cvt_pk_bf16_f32 v182, v176, v177
	v_sub_u32_e32 v176, s15, v186
	v_ashrrev_i32_e32 v179, 31, v178
	v_ashrrev_i32_e32 v177, 31, v176
	v_lshlrev_b64 v[178:179], 11, v[178:179]
	v_lshlrev_b64 v[176:177], 11, v[176:177]
	v_lshl_add_u64 v[178:179], s[24:25], 0, v[178:179]
	v_lshl_add_u64 v[176:177], s[24:25], 0, v[176:177]
	v_lshl_add_u64 v[178:179], v[178:179], 0, v[202:203]
	v_cvt_pk_bf16_f32 v183, v180, v181
	v_lshl_add_u64 v[176:177], v[176:177], 0, v[202:203]
	v_lshlrev_b64 v[180:181], 12, v[190:191]
	global_store_dwordx2 v[178:179], v[184:185], off
	global_store_dwordx2 v[176:177], v[182:183], off
	v_lshl_add_u64 v[180:181], s[26:27], 0, v[180:181]
	v_lshl_add_u64 v[180:181], v[180:181], 0, v[198:199]
	s_waitcnt vmcnt(5)
	v_mov_b64_e32 v[182:183], v[232:233]
	v_mov_b64_e32 v[184:185], v[234:235]
	v_add_u32_e32 v236, 0xa0, v206
	v_add_u32_e32 v236, s16, v236
	v_ashrrev_i32_e32 v237, 31, v236
	v_lshlrev_b64 v[236:237], 12, v[236:237]
	v_lshl_add_u64 v[236:237], s[26:27], 0, v[236:237]
	v_lshl_add_u64 v[236:237], v[236:237], 0, v[198:199]
	global_load_dwordx4 v[228:231], v[236:237], off nt
	v_pk_add_f32 v[186:187], v[200:201], v[184:185]
	v_pk_add_f32 v[188:189], v[204:205], v[182:183]
	v_sub_f32_e32 v182, v186, v62
	v_sub_f32_e32 v184, v188, v60
	v_sub_f32_e32 v185, v189, v61
	v_sub_f32_e32 v183, v187, v63
	v_cvt_pk_bf16_f32 v184, v184, v185
	v_cvt_pk_bf16_f32 v185, v182, v183
	v_add_u32_e32 v182, s16, v190
	v_ashrrev_i32_e32 v183, 31, v182
	v_lshlrev_b64 v[182:183], 11, v[182:183]
	v_lshl_add_u64 v[182:183], s[24:25], 0, v[182:183]
	v_lshl_add_u64 v[182:183], v[182:183], 0, v[202:203]
	global_store_dwordx2 v[182:183], v[184:185], off
	v_sub_u32_e32 v184, s15, v192
	v_ashrrev_i32_e32 v185, 31, v184
	s_and_saveexec_b64 s[0:1], s[10:11]
	s_cbranch_execz .LBB0_132
	v_pk_add_f32 v[186:187], v[62:63], v[186:187]
	v_pk_add_f32 v[188:189], v[60:61], v[188:189]
	s_nop 0
	v_cvt_pk_bf16_f32 v188, v188, v189
	v_cvt_pk_bf16_f32 v189, v186, v187
	v_lshlrev_b64 v[186:187], 11, v[184:185]
	v_lshl_add_u64 v[186:187], s[24:25], 0, v[186:187]
	v_lshl_add_u64 v[186:187], v[138:139], 1, v[186:187]
	global_store_dwordx2 v[186:187], v[188:189], off
.LBB0_132:
	s_or_b64 exec, exec, s[0:1]
	v_add_u32_e32 v207, 0x90, v206
	v_add_u32_e32 v186, s16, v207
	v_ashrrev_i32_e32 v187, 31, v186
	v_lshlrev_b64 v[188:189], 12, v[186:187]
	v_lshl_add_u64 v[188:189], s[26:27], 0, v[188:189]
	v_lshl_add_u64 v[188:189], v[188:189], 0, v[198:199]
	s_waitcnt vmcnt(5)
	v_mov_b64_e32 v[190:191], v[246:247]
	v_mov_b64_e32 v[192:193], v[248:249]
	v_add_u32_e32 v236, 0xb0, v206
	v_add_u32_e32 v236, s16, v236
	v_ashrrev_i32_e32 v237, 31, v236
	v_lshlrev_b64 v[236:237], 12, v[236:237]
	v_lshl_add_u64 v[236:237], s[26:27], 0, v[236:237]
	v_lshl_add_u64 v[236:237], v[236:237], 0, v[198:199]
	global_load_dwordx4 v[232:235], v[236:237], off nt
	v_add_u32_e32 v186, s16, v186
	s_mov_b32 s0, 0x3c800000
	v_pk_add_f32 v[192:193], v[200:201], v[192:193]
	s_nop 0
	v_sub_f32_e32 v187, v192, v54
	v_pk_add_f32 v[194:195], v[204:205], v[190:191]
	v_sub_f32_e32 v190, v193, v55
	v_cvt_pk_bf16_f32 v197, v187, v190
	v_ashrrev_i32_e32 v187, 31, v186
	v_lshlrev_b64 v[186:187], 11, v[186:187]
	v_sub_f32_e32 v191, v194, v52
	v_sub_f32_e32 v196, v195, v53
	v_lshl_add_u64 v[186:187], s[24:25], 0, v[186:187]
	v_cvt_pk_bf16_f32 v196, v191, v196
	v_lshl_add_u64 v[190:191], v[186:187], 0, v[202:203]
	v_pk_add_f32 v[186:187], v[54:55], v[192:193]
	v_pk_add_f32 v[192:193], v[52:53], v[194:195]
	global_store_dwordx2 v[190:191], v[196:197], off
	v_cvt_pk_bf16_f32 v192, v192, v193
	v_cvt_pk_bf16_f32 v193, v186, v187
	v_sub_u32_e32 v186, s15, v207
	v_ashrrev_i32_e32 v187, 31, v186
	v_lshlrev_b64 v[186:187], 11, v[186:187]
	v_add_u32_e32 v207, 0xa0, v206
	v_lshl_add_u64 v[186:187], s[24:25], 0, v[186:187]
	v_add_u32_e32 v208, s16, v207
	v_lshl_add_u64 v[186:187], v[186:187], 0, v[202:203]
	v_ashrrev_i32_e32 v209, 31, v208
	global_store_dwordx2 v[186:187], v[192:193], off
	v_lshlrev_b64 v[192:193], 12, v[208:209]
	v_lshl_add_u64 v[192:193], s[26:27], 0, v[192:193]
	v_lshl_add_u64 v[192:193], v[192:193], 0, v[198:199]
	s_waitcnt vmcnt(5)
	v_mov_b64_e32 v[194:195], v[228:229]
	v_mov_b64_e32 v[196:197], v[230:231]
	v_pk_add_f32 v[210:211], v[200:201], v[196:197]
	v_pk_add_f32 v[194:195], v[204:205], v[194:195]
	v_sub_f32_e32 v196, v210, v38
	v_sub_f32_e32 v209, v194, v36
	v_sub_f32_e32 v241, v195, v37
	v_pk_add_f32 v[194:195], v[36:37], v[194:195]
	v_sub_f32_e32 v197, v211, v39
	v_cvt_pk_bf16_f32 v242, v209, v241
	v_cvt_pk_bf16_f32 v243, v196, v197
	v_add_u32_e32 v196, s16, v208
	v_pk_add_f32 v[208:209], v[38:39], v[210:211]
	v_cvt_pk_bf16_f32 v210, v194, v195
	v_sub_u32_e32 v194, s15, v207
	v_ashrrev_i32_e32 v197, 31, v196
	v_ashrrev_i32_e32 v195, 31, v194
	v_lshlrev_b64 v[196:197], 11, v[196:197]
	v_lshlrev_b64 v[194:195], 11, v[194:195]
	v_lshl_add_u64 v[196:197], s[24:25], 0, v[196:197]
	v_lshl_add_u64 v[194:195], s[24:25], 0, v[194:195]
	v_lshl_add_u64 v[196:197], v[196:197], 0, v[202:203]
	v_lshl_add_u64 v[194:195], v[194:195], 0, v[202:203]
	v_add_u32_e32 v241, 0xb0, v206
	global_store_dwordx2 v[196:197], v[242:243], off
	v_cvt_pk_bf16_f32 v211, v208, v209
	global_store_dwordx2 v[194:195], v[210:211], off
	v_add_u32_e32 v210, s16, v241
	v_ashrrev_i32_e32 v211, 31, v210
	v_lshlrev_b64 v[206:207], 12, v[210:211]
	v_lshl_add_u64 v[206:207], s[26:27], 0, v[206:207]
	v_lshl_add_u64 v[198:199], v[206:207], 0, v[198:199]
	s_waitcnt vmcnt(4)
	v_mov_b64_e32 v[206:207], v[232:233]
	v_mov_b64_e32 v[208:209], v[234:235]
	v_pk_add_f32 v[208:209], v[200:201], v[208:209]
	v_pk_add_f32 v[204:205], v[204:205], v[206:207]
	v_sub_f32_e32 v200, v208, v22
	v_sub_f32_e32 v206, v204, v20
	v_sub_f32_e32 v207, v205, v21
	v_sub_f32_e32 v201, v209, v23
	v_cvt_pk_bf16_f32 v206, v206, v207
	v_cvt_pk_bf16_f32 v207, v200, v201
	v_add_u32_e32 v200, s16, v210
	v_ashrrev_i32_e32 v201, 31, v200
	v_lshlrev_b64 v[200:201], 11, v[200:201]
	v_lshl_add_u64 v[200:201], s[24:25], 0, v[200:201]
	v_lshl_add_u64 v[200:201], v[200:201], 0, v[202:203]
	global_store_dwordx2 v[200:201], v[206:207], off
	v_pk_add_f32 v[206:207], v[22:23], v[208:209]
	v_pk_add_f32 v[204:205], v[20:21], v[204:205]
	s_nop 0
	v_cvt_pk_bf16_f32 v204, v204, v205
	v_cvt_pk_bf16_f32 v205, v206, v207
	v_sub_u32_e32 v206, s15, v241
	v_ashrrev_i32_e32 v207, 31, v206
	v_lshlrev_b64 v[206:207], 11, v[206:207]
	v_lshl_add_u64 v[206:207], s[24:25], 0, v[206:207]
	v_lshl_add_u64 v[202:203], v[206:207], 0, v[202:203]
	global_store_dwordx2 v[202:203], v[204:205], off
	global_load_dwordx4 v[204:207], v[160:161], off offset:64
	global_load_dwordx4 v[242:245], v[158:159], off offset:64 nt
	global_load_dwordx4 v[116:119], v[162:163], off offset:64 nt
	global_load_dwordx4 v[104:107], v[168:169], off offset:64 nt
	global_load_dwordx4 v[88:91], v[174:175], off offset:64 nt
	global_load_dwordx4 v[60:63], v[180:181], off offset:64 nt
	global_load_dwordx4 v[52:55], v[188:189], off offset:64 nt
	global_load_dwordx4 v[36:39], v[192:193], off offset:64 nt
	global_load_dwordx4 v[20:23], v[198:199], off offset:64 nt
	s_waitcnt vmcnt(7) lgkmcnt(0)
	v_pk_mul_f32 v[206:207], v[206:207], s[0:1] op_sel_hi:[1,0]
	v_pk_mul_f32 v[208:209], v[204:205], s[0:1] op_sel_hi:[1,0]
	v_xor_b32_e32 v204, 0x80000000, v206
	v_xor_b32_e32 v205, 0x80000000, v207
	v_xor_b32_e32 v210, 0x80000000, v208
	v_xor_b32_e32 v211, 0x80000000, v209
	v_cndmask_b32_e64 v205, v205, v207, s[8:9]
	v_cndmask_b32_e64 v204, v204, v206, s[8:9]
	v_cndmask_b32_e64 v207, v211, v209, s[8:9]
	v_cndmask_b32_e64 v206, v210, v208, s[8:9]
	v_pk_add_f32 v[208:209], v[244:245], v[204:205]
	v_pk_add_f32 v[210:211], v[242:243], v[206:207]
	v_sub_f32_e32 v243, v209, v123
	v_sub_f32_e32 v242, v210, v120
	v_sub_f32_e32 v241, v208, v122
	v_sub_f32_e32 v244, v211, v121
	v_cvt_pk_bf16_f32 v242, v242, v244
	v_cvt_pk_bf16_f32 v243, v241, v243
	global_store_dwordx2 v[156:157], v[242:243], off offset:32
	s_and_saveexec_b64 s[0:1], vcc
	s_cbranch_execz .LBB0_134
	v_pk_add_f32 v[208:209], v[122:123], v[208:209]
	v_pk_add_f32 v[210:211], v[120:121], v[210:211]
	s_nop 0
	v_cvt_pk_bf16_f32 v210, v210, v211
	v_cvt_pk_bf16_f32 v211, v208, v209
	v_lshlrev_b64 v[208:209], 11, v[154:155]
	v_lshl_add_u64 v[208:209], s[24:25], 0, v[208:209]
	v_lshl_add_u64 v[208:209], v[138:139], 1, v[208:209]
	global_store_dwordx2 v[208:209], v[210:211], off offset:32
.LBB0_134:
	s_or_b64 exec, exec, s[0:1]
	s_waitcnt vmcnt(8)
	v_mov_b64_e32 v[208:209], v[116:117]
	v_mov_b64_e32 v[210:211], v[118:119]
	v_pk_add_f32 v[210:211], v[204:205], v[210:211]
	v_pk_add_f32 v[208:209], v[206:207], v[208:209]
	v_sub_f32_e32 v243, v211, v115
	v_sub_f32_e32 v242, v208, v112
	v_sub_f32_e32 v244, v209, v113
	v_pk_add_f32 v[208:209], v[112:113], v[208:209]
	v_sub_f32_e32 v241, v210, v114
	v_cvt_pk_bf16_f32 v242, v242, v244
	v_cvt_pk_bf16_f32 v243, v241, v243
	global_store_dwordx2 v[166:167], v[242:243], off offset:32
	v_pk_add_f32 v[210:211], v[114:115], v[210:211]
	v_cvt_pk_bf16_f32 v208, v208, v209
	s_nop 0
	v_cvt_pk_bf16_f32 v209, v210, v211
	global_store_dwordx2 v[164:165], v[208:209], off offset:32
	s_waitcnt vmcnt(9)
	v_mov_b64_e32 v[208:209], v[104:105]
	v_mov_b64_e32 v[210:211], v[106:107]
	v_pk_add_f32 v[210:211], v[204:205], v[210:211]
	v_pk_add_f32 v[208:209], v[206:207], v[208:209]
	v_sub_f32_e32 v243, v211, v99
	v_sub_f32_e32 v242, v208, v96
	v_sub_f32_e32 v244, v209, v97
	v_pk_add_f32 v[208:209], v[96:97], v[208:209]
	v_sub_f32_e32 v241, v210, v98
	v_cvt_pk_bf16_f32 v242, v242, v244
	v_cvt_pk_bf16_f32 v243, v241, v243
	global_store_dwordx2 v[172:173], v[242:243], off offset:32
	v_pk_add_f32 v[210:211], v[98:99], v[210:211]
	v_cvt_pk_bf16_f32 v208, v208, v209
	s_nop 0
	v_cvt_pk_bf16_f32 v209, v210, v211
	global_store_dwordx2 v[170:171], v[208:209], off offset:32
	s_waitcnt vmcnt(10)
	v_mov_b64_e32 v[208:209], v[88:89]
	v_mov_b64_e32 v[210:211], v[90:91]
	v_pk_add_f32 v[210:211], v[204:205], v[210:211]
	v_pk_add_f32 v[208:209], v[206:207], v[208:209]
	v_sub_f32_e32 v243, v211, v83
	v_sub_f32_e32 v242, v208, v80
	v_sub_f32_e32 v244, v209, v81
	v_pk_add_f32 v[208:209], v[80:81], v[208:209]
	v_sub_f32_e32 v241, v210, v82
	v_cvt_pk_bf16_f32 v242, v242, v244
	v_cvt_pk_bf16_f32 v243, v241, v243
	global_store_dwordx2 v[178:179], v[242:243], off offset:32
	v_pk_add_f32 v[210:211], v[82:83], v[210:211]
	v_cvt_pk_bf16_f32 v208, v208, v209
	s_nop 0
	v_cvt_pk_bf16_f32 v209, v210, v211
	global_store_dwordx2 v[176:177], v[208:209], off offset:32
	s_waitcnt vmcnt(11)
	v_mov_b64_e32 v[242:243], v[60:61]
	v_mov_b64_e32 v[244:245], v[62:63]
	v_pk_add_f32 v[208:209], v[204:205], v[244:245]
	v_pk_add_f32 v[210:211], v[206:207], v[242:243]
	v_sub_f32_e32 v243, v209, v59
	v_sub_f32_e32 v242, v210, v56
	v_sub_f32_e32 v241, v208, v58
	v_sub_f32_e32 v244, v211, v57
	v_cvt_pk_bf16_f32 v242, v242, v244
	v_cvt_pk_bf16_f32 v243, v241, v243
	global_store_dwordx2 v[182:183], v[242:243], off offset:32
	s_and_saveexec_b64 s[0:1], s[10:11]
	s_cbranch_execz .LBB0_136
	v_pk_add_f32 v[208:209], v[58:59], v[208:209]
	v_pk_add_f32 v[210:211], v[56:57], v[210:211]
	s_nop 0
	v_cvt_pk_bf16_f32 v210, v210, v211
	v_cvt_pk_bf16_f32 v211, v208, v209
	v_lshlrev_b64 v[208:209], 11, v[184:185]
	v_lshl_add_u64 v[208:209], s[24:25], 0, v[208:209]
	v_lshl_add_u64 v[208:209], v[138:139], 1, v[208:209]
	global_store_dwordx2 v[208:209], v[210:211], off offset:32
.LBB0_136:
	s_or_b64 exec, exec, s[0:1]
	s_waitcnt vmcnt(12)
	v_mov_b64_e32 v[208:209], v[52:53]
	v_mov_b64_e32 v[210:211], v[54:55]
	s_mov_b32 s0, 0x3c800000
	v_pk_add_f32 v[210:211], v[204:205], v[210:211]
	v_pk_add_f32 v[208:209], v[206:207], v[208:209]
	v_sub_f32_e32 v243, v211, v51
	v_sub_f32_e32 v242, v208, v48
	v_sub_f32_e32 v244, v209, v49
	v_pk_add_f32 v[208:209], v[48:49], v[208:209]
	v_sub_f32_e32 v241, v210, v50
	v_cvt_pk_bf16_f32 v242, v242, v244
	v_cvt_pk_bf16_f32 v243, v241, v243
	global_store_dwordx2 v[190:191], v[242:243], off offset:32
	v_pk_add_f32 v[210:211], v[50:51], v[210:211]
	v_cvt_pk_bf16_f32 v208, v208, v209
	s_nop 0
	v_cvt_pk_bf16_f32 v209, v210, v211
	global_store_dwordx2 v[186:187], v[208:209], off offset:32
	s_waitcnt vmcnt(13)
	v_mov_b64_e32 v[208:209], v[36:37]
	v_mov_b64_e32 v[210:211], v[38:39]
	v_pk_add_f32 v[210:211], v[204:205], v[210:211]
	v_pk_add_f32 v[208:209], v[206:207], v[208:209]
	v_sub_f32_e32 v243, v211, v35
	v_sub_f32_e32 v242, v208, v32
	v_sub_f32_e32 v244, v209, v33
	v_pk_add_f32 v[208:209], v[32:33], v[208:209]
	v_sub_f32_e32 v241, v210, v34
	v_cvt_pk_bf16_f32 v242, v242, v244
	v_cvt_pk_bf16_f32 v243, v241, v243
	global_store_dwordx2 v[196:197], v[242:243], off offset:32
	v_pk_add_f32 v[210:211], v[34:35], v[210:211]
	v_cvt_pk_bf16_f32 v208, v208, v209
	s_nop 0
	v_cvt_pk_bf16_f32 v209, v210, v211
	global_store_dwordx2 v[194:195], v[208:209], off offset:32
	s_waitcnt vmcnt(14)
	v_mov_b64_e32 v[208:209], v[20:21]
	v_mov_b64_e32 v[210:211], v[22:23]
	v_pk_add_f32 v[204:205], v[204:205], v[210:211]
	v_pk_add_f32 v[206:207], v[206:207], v[208:209]
	v_sub_f32_e32 v209, v204, v18
	v_sub_f32_e32 v208, v206, v16
	v_sub_f32_e32 v211, v207, v17
	v_pk_add_f32 v[206:207], v[16:17], v[206:207]
	v_sub_f32_e32 v210, v205, v19
	v_cvt_pk_bf16_f32 v208, v208, v211
	v_cvt_pk_bf16_f32 v209, v209, v210
	global_store_dwordx2 v[200:201], v[208:209], off offset:32
	v_pk_add_f32 v[204:205], v[18:19], v[204:205]
	v_cvt_pk_bf16_f32 v206, v206, v207
	s_nop 0
	v_cvt_pk_bf16_f32 v207, v204, v205
	global_store_dwordx2 v[202:203], v[206:207], off offset:32
	global_load_dwordx4 v[204:207], v[160:161], off offset:512
	global_load_dwordx4 v[242:245], v[158:159], off offset:512 nt
	global_load_dwordx4 v[112:115], v[162:163], off offset:512 nt
	global_load_dwordx4 v[96:99], v[168:169], off offset:512 nt
	global_load_dwordx4 v[80:83], v[174:175], off offset:512 nt
	global_load_dwordx4 v[56:59], v[180:181], off offset:512 nt
	global_load_dwordx4 v[48:51], v[188:189], off offset:512 nt
	global_load_dwordx4 v[32:35], v[192:193], off offset:512 nt
	global_load_dwordx4 v[16:19], v[198:199], off offset:512 nt
	s_waitcnt vmcnt(7) lgkmcnt(0)
	v_pk_mul_f32 v[206:207], v[206:207], s[0:1] op_sel_hi:[1,0]
	v_pk_mul_f32 v[208:209], v[204:205], s[0:1] op_sel_hi:[1,0]
	v_xor_b32_e32 v204, 0x80000000, v206
	v_xor_b32_e32 v205, 0x80000000, v207
	v_xor_b32_e32 v210, 0x80000000, v208
	v_xor_b32_e32 v211, 0x80000000, v209
	v_cndmask_b32_e64 v205, v205, v207, s[8:9]
	v_cndmask_b32_e64 v204, v204, v206, s[8:9]
	v_cndmask_b32_e64 v207, v211, v209, s[8:9]
	v_cndmask_b32_e64 v206, v210, v208, s[8:9]
	v_pk_add_f32 v[208:209], v[244:245], v[204:205]
	v_pk_add_f32 v[210:211], v[242:243], v[206:207]
	v_sub_f32_e32 v243, v209, v111
	v_sub_f32_e32 v242, v210, v108
	v_sub_f32_e32 v241, v208, v110
	v_sub_f32_e32 v244, v211, v109
	v_cvt_pk_bf16_f32 v242, v242, v244
	v_cvt_pk_bf16_f32 v243, v241, v243
	global_store_dwordx2 v[156:157], v[242:243], off offset:256
	s_and_saveexec_b64 s[0:1], vcc
	s_cbranch_execz .LBB0_138
	v_pk_add_f32 v[208:209], v[110:111], v[208:209]
	v_pk_add_f32 v[210:211], v[108:109], v[210:211]
	s_nop 0
	v_cvt_pk_bf16_f32 v210, v210, v211
	v_cvt_pk_bf16_f32 v211, v208, v209
	v_lshlrev_b64 v[208:209], 11, v[154:155]
	v_lshl_add_u64 v[208:209], s[24:25], 0, v[208:209]
	v_lshl_add_u64 v[208:209], v[138:139], 1, v[208:209]
	global_store_dwordx2 v[208:209], v[210:211], off offset:256
.LBB0_138:
	s_or_b64 exec, exec, s[0:1]
	s_waitcnt vmcnt(8)
	v_mov_b64_e32 v[208:209], v[112:113]
	v_mov_b64_e32 v[210:211], v[114:115]
	v_pk_add_f32 v[210:211], v[204:205], v[210:211]
	v_pk_add_f32 v[208:209], v[206:207], v[208:209]
	v_sub_f32_e32 v243, v211, v95
	v_sub_f32_e32 v242, v208, v92
	v_sub_f32_e32 v244, v209, v93
	v_pk_add_f32 v[208:209], v[92:93], v[208:209]
	v_sub_f32_e32 v241, v210, v94
	v_cvt_pk_bf16_f32 v242, v242, v244
	v_cvt_pk_bf16_f32 v243, v241, v243
	global_store_dwordx2 v[166:167], v[242:243], off offset:256
	v_pk_add_f32 v[210:211], v[94:95], v[210:211]
	v_cvt_pk_bf16_f32 v208, v208, v209
	s_nop 0
	v_cvt_pk_bf16_f32 v209, v210, v211
	global_store_dwordx2 v[164:165], v[208:209], off offset:256
	s_waitcnt vmcnt(9)
	v_mov_b64_e32 v[208:209], v[96:97]
	v_mov_b64_e32 v[210:211], v[98:99]
	v_pk_add_f32 v[210:211], v[204:205], v[210:211]
	v_pk_add_f32 v[208:209], v[206:207], v[208:209]
	v_sub_f32_e32 v243, v211, v79
	v_sub_f32_e32 v242, v208, v76
	v_sub_f32_e32 v244, v209, v77
	v_pk_add_f32 v[208:209], v[76:77], v[208:209]
	v_sub_f32_e32 v241, v210, v78
	v_cvt_pk_bf16_f32 v242, v242, v244
	v_cvt_pk_bf16_f32 v243, v241, v243
	global_store_dwordx2 v[172:173], v[242:243], off offset:256
	v_pk_add_f32 v[210:211], v[78:79], v[210:211]
	v_cvt_pk_bf16_f32 v208, v208, v209
	s_nop 0
	v_cvt_pk_bf16_f32 v209, v210, v211
	global_store_dwordx2 v[170:171], v[208:209], off offset:256
	s_waitcnt vmcnt(10)
	v_mov_b64_e32 v[208:209], v[80:81]
	v_mov_b64_e32 v[210:211], v[82:83]
	v_pk_add_f32 v[210:211], v[204:205], v[210:211]
	v_pk_add_f32 v[208:209], v[206:207], v[208:209]
	v_sub_f32_e32 v243, v211, v71
	v_sub_f32_e32 v242, v208, v68
	v_sub_f32_e32 v244, v209, v69
	v_pk_add_f32 v[208:209], v[68:69], v[208:209]
	v_sub_f32_e32 v241, v210, v70
	v_cvt_pk_bf16_f32 v242, v242, v244
	v_cvt_pk_bf16_f32 v243, v241, v243
	global_store_dwordx2 v[178:179], v[242:243], off offset:256
	v_pk_add_f32 v[210:211], v[70:71], v[210:211]
	v_cvt_pk_bf16_f32 v208, v208, v209
	s_nop 0
	v_cvt_pk_bf16_f32 v209, v210, v211
	global_store_dwordx2 v[176:177], v[208:209], off offset:256
	s_waitcnt vmcnt(11)
	v_mov_b64_e32 v[242:243], v[56:57]
	v_mov_b64_e32 v[244:245], v[58:59]
	v_pk_add_f32 v[208:209], v[204:205], v[244:245]
	v_pk_add_f32 v[210:211], v[206:207], v[242:243]
	v_sub_f32_e32 v243, v209, v47
	v_sub_f32_e32 v242, v210, v44
	v_sub_f32_e32 v241, v208, v46
	v_sub_f32_e32 v244, v211, v45
	v_cvt_pk_bf16_f32 v242, v242, v244
	v_cvt_pk_bf16_f32 v243, v241, v243
	global_store_dwordx2 v[182:183], v[242:243], off offset:256
	s_and_saveexec_b64 s[0:1], s[10:11]
	s_cbranch_execz .LBB0_140
	v_pk_add_f32 v[208:209], v[46:47], v[208:209]
	v_pk_add_f32 v[210:211], v[44:45], v[210:211]
	s_nop 0
	v_cvt_pk_bf16_f32 v210, v210, v211
	v_cvt_pk_bf16_f32 v211, v208, v209
	v_lshlrev_b64 v[208:209], 11, v[184:185]
	v_lshl_add_u64 v[208:209], s[24:25], 0, v[208:209]
	v_lshl_add_u64 v[208:209], v[138:139], 1, v[208:209]
	global_store_dwordx2 v[208:209], v[210:211], off offset:256
.LBB0_140:
	s_or_b64 exec, exec, s[0:1]
	s_waitcnt vmcnt(12)
	v_mov_b64_e32 v[208:209], v[48:49]
	v_mov_b64_e32 v[210:211], v[50:51]
	s_mov_b32 s0, 0x3c800000
	v_pk_add_f32 v[210:211], v[204:205], v[210:211]
	v_pk_add_f32 v[208:209], v[206:207], v[208:209]
	v_sub_f32_e32 v243, v211, v31
	v_sub_f32_e32 v242, v208, v28
	v_sub_f32_e32 v244, v209, v29
	v_pk_add_f32 v[208:209], v[28:29], v[208:209]
	v_sub_f32_e32 v241, v210, v30
	v_cvt_pk_bf16_f32 v242, v242, v244
	v_cvt_pk_bf16_f32 v243, v241, v243
	global_store_dwordx2 v[190:191], v[242:243], off offset:256
	v_pk_add_f32 v[210:211], v[30:31], v[210:211]
	v_cvt_pk_bf16_f32 v208, v208, v209
	s_nop 0
	v_cvt_pk_bf16_f32 v209, v210, v211
	global_store_dwordx2 v[186:187], v[208:209], off offset:256
	s_waitcnt vmcnt(13)
	v_mov_b64_e32 v[208:209], v[32:33]
	v_mov_b64_e32 v[210:211], v[34:35]
	v_pk_add_f32 v[210:211], v[204:205], v[210:211]
	v_pk_add_f32 v[208:209], v[206:207], v[208:209]
	v_sub_f32_e32 v243, v211, v15
	v_sub_f32_e32 v242, v208, v12
	v_sub_f32_e32 v244, v209, v13
	v_pk_add_f32 v[208:209], v[12:13], v[208:209]
	v_sub_f32_e32 v241, v210, v14
	v_cvt_pk_bf16_f32 v242, v242, v244
	v_cvt_pk_bf16_f32 v243, v241, v243
	global_store_dwordx2 v[196:197], v[242:243], off offset:256
	v_pk_add_f32 v[210:211], v[14:15], v[210:211]
	v_cvt_pk_bf16_f32 v208, v208, v209
	s_nop 0
	v_cvt_pk_bf16_f32 v209, v210, v211
	global_store_dwordx2 v[194:195], v[208:209], off offset:256
	s_waitcnt vmcnt(14)
	v_mov_b64_e32 v[208:209], v[16:17]
	v_mov_b64_e32 v[210:211], v[18:19]
	v_pk_add_f32 v[204:205], v[204:205], v[210:211]
	v_pk_add_f32 v[206:207], v[206:207], v[208:209]
	v_sub_f32_e32 v209, v204, v6
	v_sub_f32_e32 v208, v206, v4
	v_sub_f32_e32 v211, v207, v5
	v_pk_add_f32 v[206:207], v[4:5], v[206:207]
	v_sub_f32_e32 v210, v205, v7
	v_cvt_pk_bf16_f32 v208, v208, v211
	v_cvt_pk_bf16_f32 v209, v209, v210
	global_store_dwordx2 v[200:201], v[208:209], off offset:256
	v_pk_add_f32 v[204:205], v[6:7], v[204:205]
	v_cvt_pk_bf16_f32 v206, v206, v207
	s_nop 0
	v_cvt_pk_bf16_f32 v207, v204, v205
	global_store_dwordx2 v[202:203], v[206:207], off offset:256
	global_load_dwordx4 v[204:207], v[160:161], off offset:576
	s_waitcnt vmcnt(0) lgkmcnt(0)
	v_pk_mul_f32 v[160:161], v[206:207], s[0:1] op_sel_hi:[1,0]
	v_pk_mul_f32 v[204:205], v[204:205], s[0:1] op_sel_hi:[1,0]
	v_xor_b32_e32 v206, 0x80000000, v160
	v_xor_b32_e32 v207, 0x80000000, v161
	v_xor_b32_e32 v208, 0x80000000, v204
	v_xor_b32_e32 v209, 0x80000000, v205
	v_cndmask_b32_e64 v161, v207, v161, s[8:9]
	v_cndmask_b32_e64 v160, v206, v160, s[8:9]
	v_cndmask_b32_e64 v205, v209, v205, s[8:9]
	v_cndmask_b32_e64 v204, v208, v204, s[8:9]
	global_load_dwordx4 v[206:209], v[158:159], off offset:576 nt
	global_load_dwordx4 v[92:95], v[162:163], off offset:576 nt
	global_load_dwordx4 v[76:79], v[168:169], off offset:576 nt
	global_load_dwordx4 v[68:71], v[174:175], off offset:576 nt
	global_load_dwordx4 v[44:47], v[180:181], off offset:576 nt
	global_load_dwordx4 v[28:31], v[188:189], off offset:576 nt
	global_load_dwordx4 v[12:15], v[192:193], off offset:576 nt
	global_load_dwordx4 v[4:7], v[198:199], off offset:576 nt
	s_waitcnt vmcnt(7) lgkmcnt(0)
	v_pk_add_f32 v[158:159], v[208:209], v[160:161]
	v_pk_add_f32 v[206:207], v[206:207], v[204:205]
	v_sub_f32_e32 v209, v158, v102
	v_sub_f32_e32 v208, v206, v100
	v_sub_f32_e32 v210, v159, v103
	v_sub_f32_e32 v211, v207, v101
	v_cvt_pk_bf16_f32 v208, v208, v211
	v_cvt_pk_bf16_f32 v209, v209, v210
	global_store_dwordx2 v[156:157], v[208:209], off offset:288
	s_and_saveexec_b64 s[0:1], vcc
	s_cbranch_execz .LBB0_142
	v_lshlrev_b64 v[154:155], 11, v[154:155]
	v_lshl_add_u64 v[154:155], s[24:25], 0, v[154:155]
	v_pk_add_f32 v[156:157], v[102:103], v[158:159]
	v_pk_add_f32 v[158:159], v[100:101], v[206:207]
	v_lshl_add_u64 v[154:155], v[138:139], 1, v[154:155]
	v_cvt_pk_bf16_f32 v158, v158, v159
	v_cvt_pk_bf16_f32 v159, v156, v157
	global_store_dwordx2 v[154:155], v[158:159], off offset:288
.LBB0_142:
	s_or_b64 exec, exec, s[0:1]
	s_waitcnt vmcnt(8)
	v_mov_b64_e32 v[154:155], v[92:93]
	v_mov_b64_e32 v[156:157], v[94:95]
	v_pk_add_f32 v[156:157], v[160:161], v[156:157]
	v_pk_add_f32 v[154:155], v[204:205], v[154:155]
	v_sub_f32_e32 v159, v156, v86
	v_sub_f32_e32 v158, v154, v84
	v_sub_f32_e32 v163, v155, v85
	v_pk_add_f32 v[154:155], v[84:85], v[154:155]
	v_sub_f32_e32 v162, v157, v87
	v_cvt_pk_bf16_f32 v158, v158, v163
	v_cvt_pk_bf16_f32 v159, v159, v162
	global_store_dwordx2 v[166:167], v[158:159], off offset:288
	v_pk_add_f32 v[156:157], v[86:87], v[156:157]
	v_cvt_pk_bf16_f32 v154, v154, v155
	s_nop 0
	v_cvt_pk_bf16_f32 v155, v156, v157
	global_store_dwordx2 v[164:165], v[154:155], off offset:288
	s_waitcnt vmcnt(9)
	v_mov_b64_e32 v[154:155], v[76:77]
	v_mov_b64_e32 v[156:157], v[78:79]
	v_pk_add_f32 v[156:157], v[160:161], v[156:157]
	v_pk_add_f32 v[154:155], v[204:205], v[154:155]
	v_sub_f32_e32 v159, v156, v74
	v_sub_f32_e32 v158, v154, v72
	v_sub_f32_e32 v163, v155, v73
	v_pk_add_f32 v[154:155], v[72:73], v[154:155]
	v_sub_f32_e32 v162, v157, v75
	v_cvt_pk_bf16_f32 v158, v158, v163
	v_cvt_pk_bf16_f32 v159, v159, v162
	global_store_dwordx2 v[172:173], v[158:159], off offset:288
	v_pk_add_f32 v[156:157], v[74:75], v[156:157]
	v_cvt_pk_bf16_f32 v154, v154, v155
	s_nop 0
	v_cvt_pk_bf16_f32 v155, v156, v157
	global_store_dwordx2 v[170:171], v[154:155], off offset:288
	s_waitcnt vmcnt(10)
	v_mov_b64_e32 v[154:155], v[68:69]
	v_mov_b64_e32 v[156:157], v[70:71]
	v_pk_add_f32 v[156:157], v[160:161], v[156:157]
	v_pk_add_f32 v[154:155], v[204:205], v[154:155]
	v_sub_f32_e32 v159, v156, v66
	v_sub_f32_e32 v158, v154, v64
	v_sub_f32_e32 v163, v155, v65
	v_pk_add_f32 v[154:155], v[64:65], v[154:155]
	v_sub_f32_e32 v162, v157, v67
	v_cvt_pk_bf16_f32 v158, v158, v163
	v_cvt_pk_bf16_f32 v159, v159, v162
	global_store_dwordx2 v[178:179], v[158:159], off offset:288
	v_pk_add_f32 v[156:157], v[66:67], v[156:157]
	v_cvt_pk_bf16_f32 v154, v154, v155
	s_nop 0
	v_cvt_pk_bf16_f32 v155, v156, v157
	global_store_dwordx2 v[176:177], v[154:155], off offset:288
	s_waitcnt vmcnt(11)
	v_mov_b64_e32 v[156:157], v[44:45]
	v_mov_b64_e32 v[158:159], v[46:47]
	v_pk_add_f32 v[154:155], v[160:161], v[158:159]
	v_pk_add_f32 v[156:157], v[204:205], v[156:157]
	v_sub_f32_e32 v159, v154, v42
	v_sub_f32_e32 v158, v156, v40
	v_sub_f32_e32 v162, v155, v43
	v_sub_f32_e32 v163, v157, v41
	v_cvt_pk_bf16_f32 v158, v158, v163
	v_cvt_pk_bf16_f32 v159, v159, v162
	global_store_dwordx2 v[182:183], v[158:159], off offset:288
	s_and_saveexec_b64 s[0:1], s[10:11]
	s_cbranch_execz .LBB0_144
	v_pk_add_f32 v[154:155], v[42:43], v[154:155]
	v_pk_add_f32 v[156:157], v[40:41], v[156:157]
	s_nop 0
	v_cvt_pk_bf16_f32 v156, v156, v157
	v_cvt_pk_bf16_f32 v157, v154, v155
	v_lshlrev_b64 v[154:155], 11, v[184:185]
	v_lshl_add_u64 v[154:155], s[24:25], 0, v[154:155]
	v_lshl_add_u64 v[154:155], v[138:139], 1, v[154:155]
	global_store_dwordx2 v[154:155], v[156:157], off offset:288
.LBB0_144:
	s_or_b64 exec, exec, s[0:1]
	s_waitcnt vmcnt(12)
	v_mov_b64_e32 v[154:155], v[28:29]
	v_mov_b64_e32 v[156:157], v[30:31]
	s_mov_b64 s[0:1], 0
	v_pk_add_f32 v[156:157], v[160:161], v[156:157]
	v_pk_add_f32 v[154:155], v[204:205], v[154:155]
	v_sub_f32_e32 v159, v156, v26
	v_sub_f32_e32 v158, v154, v24
	v_sub_f32_e32 v163, v155, v25
	v_pk_add_f32 v[154:155], v[24:25], v[154:155]
	v_sub_f32_e32 v162, v157, v27
	v_cvt_pk_bf16_f32 v158, v158, v163
	v_cvt_pk_bf16_f32 v159, v159, v162
	global_store_dwordx2 v[190:191], v[158:159], off offset:288
	v_pk_add_f32 v[156:157], v[26:27], v[156:157]
	v_cvt_pk_bf16_f32 v154, v154, v155
	s_nop 0
	v_cvt_pk_bf16_f32 v155, v156, v157
	global_store_dwordx2 v[186:187], v[154:155], off offset:288
	s_waitcnt vmcnt(13)
	v_mov_b64_e32 v[154:155], v[12:13]
	v_mov_b64_e32 v[156:157], v[14:15]
	v_pk_add_f32 v[156:157], v[160:161], v[156:157]
	v_pk_add_f32 v[154:155], v[204:205], v[154:155]
	v_sub_f32_e32 v159, v156, v10
	v_sub_f32_e32 v158, v154, v8
	v_sub_f32_e32 v163, v155, v9
	v_pk_add_f32 v[154:155], v[8:9], v[154:155]
	v_sub_f32_e32 v162, v157, v11
	v_cvt_pk_bf16_f32 v158, v158, v163
	v_cvt_pk_bf16_f32 v159, v159, v162
	global_store_dwordx2 v[196:197], v[158:159], off offset:288
	v_pk_add_f32 v[156:157], v[10:11], v[156:157]
	v_cvt_pk_bf16_f32 v154, v154, v155
	s_nop 0
	v_cvt_pk_bf16_f32 v155, v156, v157
	global_store_dwordx2 v[194:195], v[154:155], off offset:288
	s_waitcnt vmcnt(14)
	v_mov_b64_e32 v[154:155], v[4:5]
	v_mov_b64_e32 v[156:157], v[6:7]
	v_pk_add_f32 v[156:157], v[160:161], v[156:157]
	v_pk_add_f32 v[154:155], v[204:205], v[154:155]
	v_sub_f32_e32 v159, v156, v2
	v_sub_f32_e32 v158, v154, v0
	v_sub_f32_e32 v161, v155, v1
	v_pk_add_f32 v[154:155], v[0:1], v[154:155]
	v_sub_f32_e32 v160, v157, v3
	v_cvt_pk_bf16_f32 v158, v158, v161
	v_cvt_pk_bf16_f32 v159, v159, v160
	global_store_dwordx2 v[200:201], v[158:159], off offset:288
	v_pk_add_f32 v[156:157], v[2:3], v[156:157]
	v_cvt_pk_bf16_f32 v154, v154, v155
	s_nop 0
	v_cvt_pk_bf16_f32 v155, v156, v157
	global_store_dwordx2 v[202:203], v[154:155], off offset:288
